# v66 + loop-edge edit (back-edge rotation 7.11): attention tile loops compute counter update and exit test before the loop-back barrier, exit path gets its own barrier copy
# speedup vs baseline: 1.0163x; 1.0043x over previous
; #define AT_LOAD(TT) do { const u16* kn_ = Kp + (size_t)((TT) << 6) * ldk; const u16* vn_ = Vt + ((TT) << 6); \
;     _Pragma("unroll") for (int pi = 0; pi < 2; ++pi) vr[pi] = *(const u32x4*)(vn_ + (size_t)64 * pi * S + voff); \
;     _Pragma("unroll") for (int pi = 0; pi < NKC; ++pi) kr[pi] = *(const u32x4*)(kn_ + 64 * pi + koff); } while (0)
; template <int DQK, int KROW, bool BIAS, bool MAPS2>
; DI void attn_core(const int t, const u16* __restrict__ Q, int ldq, const u16* __restrict__ Kp, int ldk, const u16* __restrict__ Vt, int q0,
;                   char* lds, const float* lut, float b31, f32x16 (&o)[4], float& l_out) {
;     ...
;   for (int kt = 0; kt < ntile; ++kt) {
;     if (kt + 1 < ntile) {
;       AT_WRITE((kt + 1) & 1);
;       if (kt + 2 < ntile) AT_LOAD(kt + 2);
;     ...
;     __syncthreads();
.LBB0_243:
	s_or_b64 exec, exec, s[92:93]
	s_add_i32 s90, s90, 64
	s_cmp_eq_u32 s94, s95
	v_subrev_u32_e32 v159, 64, v159
	s_cbranch_scc1 .Lrot_diff_exit
	s_mov_b32 s96, s95
	s_add_i32 s95, s96, 1
	s_cmp_ge_i32 s95, s94
	s_waitcnt lgkmcnt(0)
	s_barrier
	s_cbranch_scc0 .LBB0_233
	s_branch .LBB0_235
.Lrot_diff_exit:
	s_waitcnt lgkmcnt(0)
	s_barrier
	s_branch .LBB0_247

; #define AT_LOAD(TT) do { const u16* kn_ = Kp + (size_t)((TT) << 6) * ldk; const u16* vn_ = Vt + ((TT) << 6); \
;     _Pragma("unroll") for (int pi = 0; pi < 2; ++pi) vr[pi] = *(const u32x4*)(vn_ + (size_t)64 * pi * S + voff); \
;     _Pragma("unroll") for (int pi = 0; pi < NKC; ++pi) kr[pi] = *(const u32x4*)(kn_ + 64 * pi + koff); } while (0)
; template <int DQK, int KROW, bool BIAS, bool MAPS2>
; DI void attn_core(const int t, const u16* __restrict__ Q, int ldq, const u16* __restrict__ Kp, int ldk, const u16* __restrict__ Vt, int q0,
;                   char* lds, const float* lut, float b31, f32x16 (&o)[4], float& l_out) {
;     ...
;   for (int kt = 0; kt < ntile; ++kt) {
;     if (kt + 1 < ntile) {
;       AT_WRITE((kt + 1) & 1);
;       if (kt + 2 < ntile) AT_LOAD(kt + 2);
;     ...
;     __syncthreads();
.LBB0_262:
	s_or_b64 exec, exec, s[90:91]
	s_add_i32 s4, s4, 64
	s_cmp_lg_u32 s2, s53
	s_cbranch_scc0 .Lrot_mla1_exit
	s_mov_b32 s93, s53
	s_add_i32 s53, s93, 1
	s_cmp_ge_u32 s53, s2
	s_waitcnt lgkmcnt(0)
	s_barrier
	s_cbranch_scc0 .LBB0_254
	s_branch .LBB0_256
.Lrot_mla1_exit:
	s_waitcnt lgkmcnt(0)
	s_barrier

; #define AT_LOAD(TT) do { const u16* kn_ = Kp + (size_t)((TT) << 6) * ldk; const u16* vn_ = Vt + ((TT) << 6); \
;     _Pragma("unroll") for (int pi = 0; pi < 2; ++pi) vr[pi] = *(const u32x4*)(vn_ + (size_t)64 * pi * S + voff); \
;     _Pragma("unroll") for (int pi = 0; pi < NKC; ++pi) kr[pi] = *(const u32x4*)(kn_ + 64 * pi + koff); } while (0)
; template <int DQK, int KROW, bool BIAS, bool MAPS2>
; DI void attn_core(const int t, const u16* __restrict__ Q, int ldq, const u16* __restrict__ Kp, int ldk, const u16* __restrict__ Vt, int q0,
;                   char* lds, const float* lut, float b31, f32x16 (&o)[4], float& l_out) {
;     ...
;   for (int kt = 0; kt < ntile; ++kt) {
;     if (kt + 1 < ntile) {
;       AT_WRITE((kt + 1) & 1);
;       if (kt + 2 < ntile) AT_LOAD(kt + 2);
;     ...
;     __syncthreads();
.LBB0_276:
	s_or_b64 exec, exec, s[90:91]
	s_add_i32 s4, s4, 64
	s_cmp_lg_u32 s2, s53
	s_cbranch_scc0 .Lrot_mla2_exit
	s_mov_b32 s63, s53
	s_add_i32 s53, s63, 1
	s_cmp_ge_u32 s53, s2
	s_waitcnt lgkmcnt(0)
	s_barrier
	s_cbranch_scc0 .LBB0_268
	s_branch .LBB0_270
